# v36: v34 + P5 deferred packs wait with vmcnt(2) (do not wait for the sub-chunk's first output store)
# speedup vs baseline: 1.0008x; 1.0008x over previous
; #define LAS __attribute__((address_space(3)))
; DI unsigned pk2(float lo, float hi) { f32x2 v = {lo, hi}; bfv2 b = __builtin_convertvector(v, bfv2); return __builtin_bit_cast(unsigned, b); }
; DI bf16_t f2bf(float x) { return (bf16_t)(pk2(x, 0.f) & 0xffffu); }
; #define MFMA16(a, b, c) __builtin_amdgcn_mfma_f32_16x16x32_bf16((a), (b), (c), 0, 0, 0)
; template <bool OUT> DI void hgrn_item(LAS unsigned char* lds, bf16_t* proj, float* hst, float* hdv, const float* normw, int item, bool dry) {
;     ...
;                 for (int r = 0; r < 4; ++r) { const int tt = 16 * ti + 4 * rq + r, ss = 16 * sj + e16; Ab[tt * TP + ss] = (sj <= ti && ss <= tt) ? f2bf(a[r]) : (bf16_t)0; }
;             }
; #pragma unroll
;             for (int ti = 0; ti < 4; ++ti) { o[ti] = (f32x4){0.f, 0.f, 0.f, 0.f};
; #pragma unroll
;                 for (int ks = 0; ks < 4; ++ks) { const LAS bf16_t* qp = Qt + (16 * ti + e16) * QP + 32 * ks + 4 * rq; const u32x2 q0 = *(const LAS u32x2*)qp, q1 = *(const LAS u32x2*)(qp + 16);
;                     u32x4 qa = {q0.x, q0.y, q1.x, q1.y};
;                     u32x4 sb; sb.x = pk2(st[2 * ks][0], st[2 * ks][1]); sb.y = pk2(st[2 * ks][2], st[2 * ks][3]); sb.z = pk2(st[2 * ks + 1][0], st[2 * ks + 1][1]); sb.w = pk2(st[2 * ks + 1][2], st[2 * ks + 1][3]);
;                     o[ti] = MFMA16(__builtin_bit_cast(bf16x8, qa), __builtin_bit_cast(bf16x8, sb), o[ti]); } }
;         }
; #pragma unroll
;         for (int dt = 0; dt < 8; ++dt) {
; #pragma unroll
;             for (int ks = 0; ks < 2; ++ks) { const bf16x8 ka = *(const LAS bf16x8*)(KtT + (16 * dt + e16) * TP + 32 * ks + 8 * rq); st[dt] = MFMA16(ka, vfr[ks], st[dt]); }
;             const f32x4 dv = *(const LAS f32x4*)(Dv + 16 * dt + 4 * rq);
;             st[dt] *= dv;
;         }
.LBB0_1170:
	v_or_b32_e32 v56, s14, v104
	v_cmp_gt_u32_e32 vcc, v120, v56
	s_or_b64 s[36:37], s[20:21], vcc
	s_nop 3
	v_cvt_pk_bf16_f32 v50, v50, s0
	v_cndmask_b32_e64 v50, v50, 0, s[36:37]
	v_mad_u64_u32 v[54:55], s[36:37], v56, s39, v[92:93]
	ds_write_b16 v54, v50
	v_or_b32_e32 v50, 1, v56
	v_cmp_gt_u32_e32 vcc, v120, v50
	s_or_b64 s[36:37], s[20:21], vcc
	v_cvt_pk_bf16_f32 v50, v51, s0
	v_cndmask_b32_e64 v50, v50, 0, s[36:37]
	ds_write_b16 v54, v50 offset:144
	v_or_b32_e32 v50, 2, v56
	v_cmp_gt_u32_e32 vcc, v120, v50
	s_or_b64 s[36:37], s[20:21], vcc
	v_cvt_pk_bf16_f32 v50, v52, s0
	v_cndmask_b32_e64 v50, v50, 0, s[36:37]
	ds_write_b16 v54, v50 offset:288
	v_or_b32_e32 v50, 3, v56
	v_cmp_gt_u32_e32 vcc, v120, v50
	s_or_b64 s[36:37], s[20:21], vcc
	v_cvt_pk_bf16_f32 v50, v53, s0
	v_cndmask_b32_e64 v50, v50, 0, s[36:37]
	ds_write_b16 v54, v50 offset:432
	ds_read2_b64 v[50:53], v115 offset1:4
	ds_read2_b64 v[54:57], v115 offset0:8 offset1:12
	s_waitcnt vmcnt(7)
	v_cvt_pk_bf16_f32 v66, v6, v7
	v_cvt_pk_bf16_f32 v67, v8, v9
	s_waitcnt vmcnt(6)
	v_cvt_pk_bf16_f32 v68, v10, v11
	v_cvt_pk_bf16_f32 v69, v12, v13
	s_waitcnt vmcnt(5)
	v_cvt_pk_bf16_f32 v70, v2, v3
	v_cvt_pk_bf16_f32 v71, v4, v5
	s_waitcnt lgkmcnt(1)
	v_mfma_f32_16x16x32_bf16 v[50:53], v[50:53], v[66:69], 0
	s_waitcnt vmcnt(4)
	v_cvt_pk_bf16_f32 v72, v18, v19
	v_cvt_pk_bf16_f32 v73, v20, v21
	s_waitcnt vmcnt(3)
	v_cvt_pk_bf16_f32 v100, v14, v15
	v_cvt_pk_bf16_f32 v101, v16, v17
	s_waitcnt lgkmcnt(0)
	v_mfma_f32_16x16x32_bf16 v[50:53], v[54:57], v[70:73], v[50:53]
	ds_read2_b64 v[54:57], v115 offset0:16 offset1:20
	s_waitcnt vmcnt(2)
	v_cvt_pk_bf16_f32 v102, v26, v27
	v_cvt_pk_bf16_f32 v103, v28, v29
	s_waitcnt vmcnt(1)
	v_cvt_pk_bf16_f32 v144, v22, v23
	v_cvt_pk_bf16_f32 v145, v24, v25
	s_waitcnt lgkmcnt(0)
	v_mfma_f32_16x16x32_bf16 v[50:53], v[54:57], v[100:103], v[50:53]
	ds_read2_b64 v[54:57], v115 offset0:24 offset1:28
	s_waitcnt vmcnt(0)
	v_cvt_pk_bf16_f32 v146, v30, v31
	v_cvt_pk_bf16_f32 v147, v32, v33
	v_lshl_add_u64 v[240:241], v[98:99], 0, s[34:35]
	v_add_co_u32_e32 v240, vcc, s47, v240
	s_nop 0
	v_addc_co_u32_e32 v241, vcc, 0, v241, vcc
	global_load_dwordx4 v[244:247], v[240:241], off offset:512
	v_add_u32_e32 v62, 0x1000, v115
	ds_read2_b64 v[58:61], v62 offset0:40 offset1:44
	s_waitcnt lgkmcnt(1)
	v_mfma_f32_16x16x32_bf16 v[54:57], v[54:57], v[144:147], v[50:53]
	s_nop 2
	ds_read2_b64 v[50:53], v62 offset0:32 offset1:36
	v_add_u32_e32 v143, 0x2000, v115
	s_waitcnt lgkmcnt(0)
	v_mfma_f32_16x16x32_bf16 v[50:53], v[50:53], v[66:69], 0
	v_mfma_f32_16x16x32_bf16 v[50:53], v[58:61], v[70:73], v[50:53]
	ds_read2_b64 v[58:61], v62 offset0:48 offset1:52
	s_waitcnt lgkmcnt(0)
	v_mfma_f32_16x16x32_bf16 v[50:53], v[58:61], v[100:103], v[50:53]
	ds_read2_b64 v[58:61], v62 offset0:56 offset1:60
	ds_read2_b64 v[62:65], v143 offset0:72 offset1:76
	s_waitcnt lgkmcnt(1)
	v_mfma_f32_16x16x32_bf16 v[58:61], v[58:61], v[144:147], v[50:53]
	s_nop 3
	ds_read2_b64 v[50:53], v143 offset0:64 offset1:68
	s_waitcnt lgkmcnt(0)
	v_mfma_f32_16x16x32_bf16 v[50:53], v[50:53], v[66:69], 0
	v_mfma_f32_16x16x32_bf16 v[50:53], v[62:65], v[70:73], v[50:53]
	ds_read2_b64 v[62:65], v143 offset0:80 offset1:84
	s_waitcnt lgkmcnt(0)
	v_mfma_f32_16x16x32_bf16 v[50:53], v[62:65], v[100:103], v[50:53]
	ds_read2_b64 v[62:65], v143 offset0:88 offset1:92
	v_add_u32_e32 v143, 0x3000, v115
	s_waitcnt lgkmcnt(0)
	v_mfma_f32_16x16x32_bf16 v[62:65], v[62:65], v[144:147], v[50:53]
	s_nop 3
	ds_read2_b64 v[50:53], v143 offset0:96 offset1:100
	s_waitcnt lgkmcnt(0)
	v_mfma_f32_16x16x32_bf16 v[50:53], v[50:53], v[66:69], 0
	ds_read2_b64 v[66:69], v143 offset0:104 offset1:108
	s_waitcnt lgkmcnt(0)
	v_mfma_f32_16x16x32_bf16 v[50:53], v[66:69], v[70:73], v[50:53]
	ds_read2_b64 v[66:69], v143 offset0:112 offset1:116
	s_waitcnt lgkmcnt(0)
	v_mfma_f32_16x16x32_bf16 v[50:53], v[66:69], v[100:103], v[50:53]
	ds_read2_b64 v[66:69], v143 offset0:120 offset1:124
	v_lshl_add_u64 v[102:103], v[98:99], 0, s[34:35]
	v_lshl_add_u64 v[100:101], v[96:97], 0, s[34:35]
	s_waitcnt lgkmcnt(0)
	v_mfma_f32_16x16x32_bf16 v[70:73], v[66:69], v[144:147], v[50:53]
	v_add_u32_e32 v66, v93, v108
	s_nop 1
	v_add_u32_e32 v67, 0x13c00, v93
	ds_read_b128 v[50:53], v66 offset:34816
	ds_read_b128 v[162:165], v66 offset:34880
	ds_read_b128 v[166:169], v67
	s_add_u32 s34, s34, 0xc8000
	s_addc_u32 s35, s35, 0
	s_cmp_lg_u32 s34, 0x320000
	ds_read_b128 v[170:173], v66 offset:37120
	ds_read_b128 v[174:177], v66 offset:37184
	ds_read_b128 v[178:181], v67 offset:64
	s_waitcnt lgkmcnt(3)
	v_mfma_f32_16x16x32_bf16 v[6:9], v[50:53], v[46:49], v[6:9]
	v_mfma_f32_16x16x32_bf16 v[6:9], v[162:165], v[42:45], v[6:9]
	s_nop 7
	v_pk_mul_f32 v[8:9], v[8:9], v[168:169]
	v_pk_mul_f32 v[6:7], v[6:7], v[166:167]
	ds_read_b128 v[50:53], v66 offset:39424
	ds_read_b128 v[162:165], v66 offset:39488
	ds_read_b128 v[166:169], v67 offset:128
	s_waitcnt lgkmcnt(3)
	v_mfma_f32_16x16x32_bf16 v[10:13], v[170:173], v[46:49], v[10:13]
	v_mfma_f32_16x16x32_bf16 v[10:13], v[174:177], v[42:45], v[10:13]
	s_nop 7
	v_pk_mul_f32 v[12:13], v[12:13], v[180:181]
	v_pk_mul_f32 v[10:11], v[10:11], v[178:179]
	ds_read_b128 v[170:173], v66 offset:41728
	ds_read_b128 v[174:177], v66 offset:41792
	ds_read_b128 v[178:181], v67 offset:192
	s_waitcnt lgkmcnt(3)
	v_mfma_f32_16x16x32_bf16 v[2:5], v[50:53], v[46:49], v[2:5]
	v_mfma_f32_16x16x32_bf16 v[2:5], v[162:165], v[42:45], v[2:5]
	s_nop 7
	v_pk_mul_f32 v[4:5], v[4:5], v[168:169]
	v_pk_mul_f32 v[2:3], v[2:3], v[166:167]
	ds_read_b128 v[50:53], v66 offset:44032
	ds_read_b128 v[162:165], v66 offset:44096
	ds_read_b128 v[166:169], v67 offset:256
	s_waitcnt lgkmcnt(3)
; #define LAS __attribute__((address_space(3)))
; #define MFMA16(a, b, c) __builtin_amdgcn_mfma_f32_16x16x32_bf16((a), (b), (c), 0, 0, 0)
; template <bool OUT> DI void hgrn_item(LAS unsigned char* lds, bf16_t* proj, float* hst, float* hdv, const float* normw, int item, bool dry) {
;     ...
;         for (int dt = 0; dt < 8; ++dt) {
; #pragma unroll
;             for (int ks = 0; ks < 2; ++ks) { const bf16x8 ka = *(const LAS bf16x8*)(KtT + (16 * dt + e16) * TP + 32 * ks + 8 * rq); st[dt] = MFMA16(ka, vfr[ks], st[dt]); }
;             const f32x4 dv = *(const LAS f32x4*)(Dv + 16 * dt + 4 * rq);
;             st[dt] *= dv;
;         }
;         u32x4 gate8[2];
;         if (OUT) {
; #pragma unroll
;             for (int j = 0; j < 2; ++j) { const int cch = tid + 512 * j; gate8[j] = *(const u32x4*)(proj + (row0 + (cch >> 4)) * NPJ + C_HG + h * 128 + 8 * (cch & 15)); }
;         }
;         __syncthreads();
;         if (OUT) {
; #pragma unroll
;             for (int ti = 0; ti < 4; ++ti)
; #pragma unroll
;                 for (int ks = 0; ks < 2; ++ks) if (2 * ks <= ti) { const bf16x8 aa = *(const LAS bf16x8*)(Ab + (16 * ti + e16) * TP + 32 * ks + 8 * rq); o[ti] = MFMA16(aa, vfr[ks], o[ti]); }
;             LAS float* Ob = (LAS float*)(lds + HOB_OFF);
; #pragma unroll
;             for (int ti = 0; ti < 4; ++ti)
; #pragma unroll
;                 for (int r = 0; r < 4; ++r) Ob[(16 * ti + 4 * rq + r) * OBP + w * 16 + e16] = o[ti][r];
	v_mfma_f32_16x16x32_bf16 v[18:21], v[170:173], v[46:49], v[18:21]
	v_mfma_f32_16x16x32_bf16 v[18:21], v[174:177], v[42:45], v[18:21]
	s_nop 7
	v_pk_mul_f32 v[20:21], v[20:21], v[180:181]
	v_pk_mul_f32 v[18:19], v[18:19], v[178:179]
	ds_read_b128 v[170:173], v66 offset:46336
	ds_read_b128 v[174:177], v66 offset:46400
	ds_read_b128 v[178:181], v67 offset:320
	s_waitcnt lgkmcnt(3)
	v_mfma_f32_16x16x32_bf16 v[14:17], v[50:53], v[46:49], v[14:17]
	v_mfma_f32_16x16x32_bf16 v[14:17], v[162:165], v[42:45], v[14:17]
	s_nop 7
	v_pk_mul_f32 v[16:17], v[16:17], v[168:169]
	v_pk_mul_f32 v[14:15], v[14:15], v[166:167]
	ds_read_b128 v[50:53], v66 offset:48640
	ds_read_b128 v[162:165], v66 offset:48704
	ds_read_b128 v[166:169], v67 offset:384
	s_waitcnt lgkmcnt(3)
	v_mfma_f32_16x16x32_bf16 v[26:29], v[170:173], v[46:49], v[26:29]
	v_mfma_f32_16x16x32_bf16 v[26:29], v[174:177], v[42:45], v[26:29]
	s_nop 7
	v_pk_mul_f32 v[28:29], v[28:29], v[180:181]
	v_pk_mul_f32 v[26:27], v[26:27], v[178:179]
	ds_read_b128 v[170:173], v66 offset:50944
	ds_read_b128 v[174:177], v66 offset:51008
	ds_read_b128 v[178:181], v67 offset:448
	s_waitcnt lgkmcnt(3)
	v_mfma_f32_16x16x32_bf16 v[22:25], v[50:53], v[46:49], v[22:25]
	v_mfma_f32_16x16x32_bf16 v[22:25], v[162:165], v[42:45], v[22:25]
	s_nop 7
	v_pk_mul_f32 v[24:25], v[24:25], v[168:169]
	v_pk_mul_f32 v[22:23], v[22:23], v[166:167]
	s_waitcnt lgkmcnt(0)
	v_mfma_f32_16x16x32_bf16 v[30:33], v[170:173], v[46:49], v[30:33]
	v_mfma_f32_16x16x32_bf16 v[30:33], v[174:177], v[42:45], v[30:33]
	s_nop 7
	v_pk_mul_f32 v[32:33], v[32:33], v[180:181]
	v_pk_mul_f32 v[30:31], v[30:31], v[178:179]
	v_add_co_u32_e32 v50, vcc, s47, v100
	s_nop 1
	v_addc_co_u32_e32 v51, vcc, 0, v101, vcc
	global_load_dwordx4 v[50:53], v[50:51], off offset:512
	s_barrier
	ds_read_b128 v[144:147], v116
	ds_read_b128 v[162:165], v116 offset:2304
	ds_read_b128 v[166:169], v116 offset:4608
	ds_read_b128 v[170:173], v116 offset:4672
	ds_read_b128 v[174:177], v116 offset:6912
	ds_read_b128 v[178:181], v116 offset:6976
	s_waitcnt lgkmcnt(5)
	v_mfma_f32_16x16x32_bf16 v[54:57], v[144:147], v[46:49], v[54:57]
	s_waitcnt lgkmcnt(4)
	v_mfma_f32_16x16x32_bf16 v[58:61], v[162:165], v[46:49], v[58:61]
	s_waitcnt lgkmcnt(3)
	v_mfma_f32_16x16x32_bf16 v[62:65], v[166:169], v[46:49], v[62:65]
	s_waitcnt lgkmcnt(2)
	v_mfma_f32_16x16x32_bf16 v[62:65], v[170:173], v[42:45], v[62:65]
	s_waitcnt lgkmcnt(1)
	v_mfma_f32_16x16x32_bf16 v[46:49], v[174:177], v[46:49], v[70:73]
	s_nop 2
	ds_write2_b32 v125, v54, v55 offset1:132
	s_waitcnt lgkmcnt(1)
	v_mfma_f32_16x16x32_bf16 v[42:45], v[178:181], v[42:45], v[46:49]
	s_nop 2
	v_add_u32_e32 v46, 0x400, v125
	ds_write2_b32 v46, v56, v57 offset0:8 offset1:140
	v_add_u32_e32 v46, 0x2000, v125
	ds_write2_b32 v46, v58, v59 offset0:64 offset1:196
	v_add_u32_e32 v46, 0x2400, v125
	ds_write2_b32 v46, v60, v61 offset0:72 offset1:204
	v_add_u32_e32 v46, 0x4200, v125
	ds_write2_b32 v46, v62, v63 offset1:132
	v_add_u32_e32 v46, 0x4600, v125
	ds_write2_b32 v46, v64, v65 offset0:8 offset1:140
	v_add_u32_e32 v46, 0x6200, v125
	ds_write2_b32 v46, v42, v43 offset0:64 offset1:196
	v_add_u32_e32 v42, 0x6600, v125
	ds_write2_b32 v42, v44, v45 offset0:72 offset1:204
	s_waitcnt lgkmcnt(0)
	s_barrier
; #define LAS __attribute__((address_space(3)))
; DI float bflo(unsigned w) { return __uint_as_float(w << 16); }
; DI float bfhi(unsigned w) { return __uint_as_float(w & 0xffff0000u); }
; DI u32x4 pack8(f32x4 a, f32x4 b) { u32x4 w; w.x = pk2(a[0], a[1]); w.y = pk2(a[2], a[3]); w.z = pk2(b[0], b[1]); w.w = pk2(b[2], b[3]); return w; }
; template <bool OUT> DI void hgrn_item(LAS unsigned char* lds, bf16_t* proj, float* hst, float* hdv, const float* normw, int item, bool dry) {
;     ...
; #pragma unroll
;             for (int j = 0; j < 2; ++j) { const int cch = tid + 512 * j, tt = cch >> 4, e0 = 8 * (cch & 15);
;                 const f32x4 a0 = *(const LAS f32x4*)(Ob + tt * OBP + e0), a1 = *(const LAS f32x4*)(Ob + tt * OBP + e0 + 4);
;                 float q = (a0[0] * a0[0] + a0[1] * a0[1]) + (a0[2] * a0[2] + a0[3] * a0[3]) + (a1[0] * a1[0] + a1[1] * a1[1]) + (a1[2] * a1[2] + a1[3] * a1[3]);
;                 q += __shfl_xor(q, 1); q += __shfl_xor(q, 2); q += __shfl_xor(q, 4); q += __shfl_xor(q, 8);
;                 const float rs = __builtin_amdgcn_rsqf(q * (1.0f / 128.0f) + 1e-6f);
;                 const f32x4 n0 = *(const f32x4*)(normw + e0), n1 = *(const f32x4*)(normw + e0 + 4); const u32x4 g = gate8[j];
;                 f32x4 y0, y1;
;                 y0[0] = a0[0] * rs * n0[0] * bflo(g.x); y0[1] = a0[1] * rs * n0[1] * bfhi(g.x); y0[2] = a0[2] * rs * n0[2] * bflo(g.y); y0[3] = a0[3] * rs * n0[3] * bfhi(g.y);
;                 y1[0] = a1[0] * rs * n1[0] * bflo(g.z); y1[1] = a1[1] * rs * n1[1] * bfhi(g.z); y1[2] = a1[2] * rs * n1[2] * bflo(g.w); y1[3] = a1[3] * rs * n1[3] * bfhi(g.w);
;                 if (!dry) *(u32x4*)(proj + (row0 + tt) * NPJ + C_HQ + h * 128 + e0) = pack8(y0, y1); }
	ds_read_b128 v[42:45], v117
	ds_read_b128 v[46:49], v117 offset:16
	s_waitcnt vmcnt(1)
	v_lshlrev_b32_e32 v64, 16, v246
	v_and_b32_e32 v65, 0xffff0000, v246
	s_waitcnt lgkmcnt(1)
	v_pk_mul_f32 v[54:55], v[44:45], v[44:45]
	v_pk_mul_f32 v[56:57], v[42:43], v[42:43]
	s_nop 0
	v_pk_mov_b32 v[58:59], v[56:57], v[54:55] op_sel:[1,0]
	v_mov_b32_e32 v57, v55
	v_pk_add_f32 v[54:55], v[58:59], v[56:57]
	s_waitcnt lgkmcnt(0)
	v_pk_mul_f32 v[56:57], v[48:49], v[48:49]
	v_pk_mul_f32 v[58:59], v[46:47], v[46:47]
	v_mov_b32_e32 v60, v56
	v_mov_b32_e32 v61, v58
	v_mov_b32_e32 v58, v57
	v_pk_add_f32 v[56:57], v[60:61], v[58:59]
	v_add_f32_e32 v54, v54, v55
	v_add_f32_e32 v54, v54, v57
	v_add_f32_e32 v54, v56, v54
	s_nop 1
	v_add_f32_dpp v54, v54, v54 quad_perm:[1,0,3,2] row_mask:0xf bank_mask:0xf
	s_nop 1
	v_add_f32_dpp v54, v54, v54 quad_perm:[2,3,0,1] row_mask:0xf bank_mask:0xf
	s_nop 1
	v_add_f32_dpp v62, v54, v54 row_half_mirror row_mask:0xf bank_mask:0xf
	s_nop 1
	v_add_f32_dpp v62, v62, v62 row_mirror row_mask:0xf bank_mask:0xf
	v_fmamk_f32 v62, v62, 0x3c000000, v118
	v_rsq_f32_e32 v62, v62
	s_nop 0
	v_pk_mul_f32 v[46:47], v[46:47], v[62:63] op_sel_hi:[1,0]
	v_pk_mul_f32 v[48:49], v[48:49], v[62:63] op_sel_hi:[1,0]
	v_pk_mul_f32 v[42:43], v[42:43], v[62:63] op_sel_hi:[1,0]
	v_pk_mul_f32 v[44:45], v[44:45], v[62:63] op_sel_hi:[1,0]
	s_waitcnt vmcnt(0)
	v_pk_mul_f32 v[42:43], v[232:233], v[42:43]
	v_pk_mul_f32 v[46:47], v[236:237], v[46:47]
	v_lshlrev_b32_e32 v58, 16, v247
	v_and_b32_e32 v59, 0xffff0000, v247
	v_pk_mul_f32 v[48:49], v[238:239], v[48:49]
	v_lshlrev_b32_e32 v54, 16, v245
	v_pk_mul_f32 v[48:49], v[48:49], v[58:59]
	v_lshlrev_b32_e32 v58, 16, v244
	v_and_b32_e32 v59, 0xffff0000, v244
	v_and_b32_e32 v55, 0xffff0000, v245
	v_pk_mul_f32 v[44:45], v[234:235], v[44:45]
	v_pk_mul_f32 v[46:47], v[46:47], v[64:65]
	v_pk_mul_f32 v[42:43], v[42:43], v[58:59]
	v_pk_mul_f32 v[44:45], v[44:45], v[54:55]
	v_cvt_pk_bf16_f32 v42, v42, v43
	v_cvt_pk_bf16_f32 v43, v44, v45
	v_cvt_pk_bf16_f32 v44, v46, v47
	v_cvt_pk_bf16_f32 v45, v48, v49
	global_store_dwordx4 v[102:103], v[42:45], off offset:1536
	ds_read_b128 v[42:45], v119
	ds_read_b128 v[46:49], v119 offset:16
	v_lshlrev_b32_e32 v64, 16, v52
	v_and_b32_e32 v65, 0xffff0000, v52
	v_lshlrev_b32_e32 v52, 16, v53
	s_waitcnt lgkmcnt(1)
	v_pk_mul_f32 v[54:55], v[44:45], v[44:45]
	v_pk_mul_f32 v[56:57], v[42:43], v[42:43]
	v_and_b32_e32 v53, 0xffff0000, v53
	v_pk_mov_b32 v[58:59], v[56:57], v[54:55] op_sel:[1,0]
	v_mov_b32_e32 v57, v55
	v_pk_add_f32 v[54:55], v[58:59], v[56:57]
	s_waitcnt lgkmcnt(0)
	v_pk_mul_f32 v[56:57], v[48:49], v[48:49]
	v_pk_mul_f32 v[58:59], v[46:47], v[46:47]
	v_mov_b32_e32 v60, v56
	v_mov_b32_e32 v61, v58
	v_mov_b32_e32 v58, v57
	v_pk_add_f32 v[56:57], v[60:61], v[58:59]
	v_add_f32_e32 v54, v54, v55
	v_add_f32_e32 v54, v54, v57
	v_add_f32_e32 v54, v56, v54
	s_nop 1
	v_add_f32_dpp v54, v54, v54 quad_perm:[1,0,3,2] row_mask:0xf bank_mask:0xf
	s_nop 1
	v_add_f32_dpp v54, v54, v54 quad_perm:[2,3,0,1] row_mask:0xf bank_mask:0xf
	s_nop 1
	v_add_f32_dpp v62, v54, v54 row_half_mirror row_mask:0xf bank_mask:0xf
	s_nop 1
	v_add_f32_dpp v62, v62, v62 row_mirror row_mask:0xf bank_mask:0xf
	v_fmamk_f32 v62, v62, 0x3c000000, v118
	v_rsq_f32_e32 v62, v62
	s_nop 0
	v_pk_mul_f32 v[48:49], v[48:49], v[62:63] op_sel_hi:[1,0]
	v_pk_mul_f32 v[46:47], v[46:47], v[62:63] op_sel_hi:[1,0]
	v_pk_mul_f32 v[42:43], v[42:43], v[62:63] op_sel_hi:[1,0]
	v_pk_mul_f32 v[44:45], v[44:45], v[62:63] op_sel_hi:[1,0]
	v_pk_mul_f32 v[42:43], v[232:233], v[42:43]
	v_pk_mul_f32 v[48:49], v[238:239], v[48:49]
	v_pk_mul_f32 v[46:47], v[236:237], v[46:47]
	v_pk_mul_f32 v[48:49], v[48:49], v[52:53]
	v_lshlrev_b32_e32 v52, 16, v50
	v_and_b32_e32 v53, 0xffff0000, v50
	v_lshlrev_b32_e32 v50, 16, v51
	v_and_b32_e32 v51, 0xffff0000, v51
	v_pk_mul_f32 v[44:45], v[234:235], v[44:45]
	v_pk_mul_f32 v[46:47], v[46:47], v[64:65]
	v_pk_mul_f32 v[42:43], v[42:43], v[52:53]
	v_pk_mul_f32 v[44:45], v[44:45], v[50:51]
	v_cvt_pk_bf16_f32 v42, v42, v43
	v_cvt_pk_bf16_f32 v43, v44, v45
	v_cvt_pk_bf16_f32 v44, v46, v47
	v_cvt_pk_bf16_f32 v45, v48, v49
	global_store_dwordx4 v[100:101], v[42:45], off offset:1536
	s_waitcnt vmcnt(2)
	v_lshl_or_b32 v129, v185, 16, v184
	v_lshl_or_b32 v127, v190, 16, v191
	v_lshl_or_b32 v131, v192, 16, v188
	v_lshl_or_b32 v128, v194, 16, v189
	v_lshl_or_b32 v133, v196, 16, v195
	v_lshl_or_b32 v135, v203, 16, v202
	v_lshl_or_b32 v134, v214, 16, v215
	v_lshl_or_b32 v34, v187, 16, v186
	v_lshl_or_b32 v35, v199, 16, v193
	v_lshl_or_b32 v36, v200, 16, v197
	v_lshl_or_b32 v130, v198, 16, v201
	v_lshl_or_b32 v37, v205, 16, v204
	v_lshl_or_b32 v132, v206, 16, v207
	v_lshl_or_b32 v137, v209, 16, v208
	v_lshl_or_b32 v38, v211, 16, v210
	v_lshl_or_b32 v139, v216, 16, v212
	v_lshl_or_b32 v136, v218, 16, v213
	v_lshl_or_b32 v141, v220, 16, v219
	v_lshl_or_b32 v39, v223, 16, v217
	v_lshl_or_b32 v40, v224, 16, v221
	v_lshl_or_b32 v138, v222, 16, v225
	v_lshl_or_b32 v142, v227, 16, v226
	v_lshl_or_b32 v41, v229, 16, v228
	v_lshl_or_b32 v140, v230, 16, v231
	v_mov_b32_e32 v46, v127
	v_mov_b32_e32 v47, v128
	v_mov_b32_e32 v49, v130
	v_mov_b32_e32 v51, v132
	v_mov_b32_e32 v52, v134
	v_mov_b32_e32 v53, v136
	v_mov_b32_e32 v54, v138
	v_mov_b32_e32 v48, v140
	v_mov_b32_e32 v42, v129
	v_mov_b32_e32 v43, v131
	v_mov_b32_e32 v44, v133
	v_mov_b32_e32 v45, v135
	v_mov_b32_e32 v50, v137
	v_mov_b32_e32 v55, v139
	v_mov_b32_e32 v56, v141
	v_mov_b32_e32 v57, v142
	s_cbranch_scc0 .LBB0_1168
